# baseline (speedup 1.0000x reference)
; __device__ __forceinline__ float softplusf_(float v) { return fmaxf(v, 0.f) + __logf(1.f + __expf(-fabsf(v))); }
; __device__ void attn_item(const Params& p, int item, u16* O) {
;     ...
;     const bool active = kt * 64 < q0 + wid * 16 + 16;
;     if (active) {
;       f32x4 s[4];
;       __builtin_amdgcn_s_setprio(1);
; #pragma unroll
;       for (int mf = 0; mf < 4; ++mf) {
;         s[mf] = f32x4{0.f, 0.f, 0.f, 0.f};
; #pragma unroll
;         for (int ks = 0; ks < 4; ++ks) {
;           bf16x8 a = *(const bf16x8*)(Ks + (mf * 16 + fr) * 136 + ks * 32 + g4 * 8);
;           s[mf] = __builtin_amdgcn_mfma_f32_16x16x32_bf16(a, qf[ks], s[mf], 0, 0, 0);
;         }
;       }
;       __builtin_amdgcn_s_setprio(0);
;       float c[4][4], T[4];
;       bool valid[4][4];
; #pragma unroll
;       for (int mf = 0; mf < 4; ++mf) {
; #pragma unroll
;         for (int r = 0; r < 4; ++r) {
;           int kk = kt * 64 + mf * 16 + g4 * 4 + r;
;           valid[mf][r] = kk < qrow;
;           c[mf][r] = valid[mf][r] ? -softplusf_(s[mf][r]) : 0.f;
;         }
.LBB0_746:
	s_waitcnt lgkmcnt(0)
	s_barrier
	v_cmp_le_i32_e32 vcc, s0, v108
	s_and_saveexec_b64 s[70:71], vcc
	s_cbranch_execz .LBB0_780
	s_setprio 1
	ds_read_b128 v[64:67], v118
	ds_read_b128 v[68:71], v118 offset:64
	ds_read_b128 v[72:75], v118 offset:4352
	ds_read_b128 v[96:99], v118 offset:4416
	ds_read_b128 v[76:79], v118 offset:128
	ds_read_b128 v[100:103], v118 offset:13184
	s_waitcnt lgkmcnt(5)
	v_mfma_f32_16x16x32_bf16 v[64:67], v[64:67], v[0:3], 0
	s_waitcnt lgkmcnt(4)
	v_mfma_f32_16x16x32_bf16 v[64:67], v[68:71], v[4:7], v[64:67]
	ds_read_b128 v[68:71], v118 offset:192
	s_waitcnt lgkmcnt(2)
	v_mfma_f32_16x16x32_bf16 v[64:67], v[76:79], v[8:11], v[64:67]
	v_mfma_f32_16x16x32_bf16 v[72:75], v[72:75], v[0:3], 0
	s_waitcnt lgkmcnt(0)
	v_mfma_f32_16x16x32_bf16 v[76:79], v[68:71], v[12:15], v[64:67]
	s_nop 4
	ds_read_b128 v[64:67], v118 offset:4480
	v_mfma_f32_16x16x32_bf16 v[68:71], v[96:99], v[4:7], v[72:75]
	ds_read_b128 v[96:99], v118 offset:8832
	s_nop 1
	ds_read_b128 v[72:75], v118 offset:4544
	s_waitcnt lgkmcnt(2)
	v_mfma_f32_16x16x32_bf16 v[64:67], v[64:67], v[8:11], v[68:71]
	s_nop 2
	ds_read_b128 v[68:71], v118 offset:8704
	s_waitcnt lgkmcnt(1)
	v_mfma_f32_16x16x32_bf16 v[72:75], v[72:75], v[12:15], v[64:67]
	s_nop 2
	ds_read_b128 v[64:67], v118 offset:8768
	s_waitcnt lgkmcnt(1)
	v_mfma_f32_16x16x32_bf16 v[68:71], v[68:71], v[0:3], 0
	s_waitcnt lgkmcnt(0)
	v_mfma_f32_16x16x32_bf16 v[64:67], v[64:67], v[4:7], v[68:71]
	s_nop 5
	ds_read_b128 v[68:71], v118 offset:8896
	v_mfma_f32_16x16x32_bf16 v[64:67], v[96:99], v[8:11], v[64:67]
	ds_read_b128 v[96:99], v118 offset:13056
	s_waitcnt lgkmcnt(1)
	v_mfma_f32_16x16x32_bf16 v[68:71], v[68:71], v[12:15], v[64:67]
	s_nop 4
	ds_read_b128 v[64:67], v118 offset:13120
	s_waitcnt lgkmcnt(1)
	v_mfma_f32_16x16x32_bf16 v[96:99], v[96:99], v[0:3], 0
	s_waitcnt lgkmcnt(0)
	v_mfma_f32_16x16x32_bf16 v[64:67], v[64:67], v[4:7], v[96:99]
	s_nop 5
	ds_read_b128 v[96:99], v118 offset:13248
	v_mfma_f32_16x16x32_bf16 v[64:67], v[100:103], v[8:11], v[64:67]
	s_waitcnt lgkmcnt(0)
	v_mfma_f32_16x16x32_bf16 v[64:67], v[96:99], v[12:15], v[64:67]
	s_setprio 0
	v_or_b32_e32 v101, s0, v109
	v_cmp_lt_i32_e32 vcc, v101, v82
	v_mov_b32_e32 v97, 0
	v_mov_b32_e32 v80, 0
	s_and_saveexec_b64 s[14:15], vcc
	s_cbranch_execz .LBB0_749
	v_mul_f32_e64 v80, |v76|, s76
	v_exp_f32_e32 v80, v80
	s_nop 0
	v_add_f32_e32 v80, 1.0, v80
	v_log_f32_e32 v80, v80
	v_max_f32_e32 v96, v76, v76
	v_max_f32_e32 v96, 0, v96
	v_mul_f32_e32 v98, 0x3f317217, v80
	v_fma_f32 v98, v80, s79, -v98
	v_fmac_f32_e32 v98, 0x3377d1cf, v80
	v_fmac_f32_e32 v98, 0x3f317217, v80
	v_mov_b32_e32 v80, v98
	v_add_f32_e32 v80, v96, v80
	v_xor_b32_e32 v80, 0x80000000, v80
.LBB0_749:
	s_or_b64 exec, exec, s[14:15]
	v_or_b32_e32 v96, 1, v101
	v_cmp_lt_i32_e64 s[12:13], v96, v82
	v_mov_b32_e32 v99, 0
	s_and_saveexec_b64 s[16:17], s[12:13]
	s_cbranch_execz .LBB0_751
	v_mul_f32_e64 v96, |v77|, s76
	v_exp_f32_e32 v96, v96
	s_nop 0
	v_add_f32_e32 v96, 1.0, v96
	v_log_f32_e32 v96, v96
	v_max_f32_e32 v98, v77, v77
	v_max_f32_e32 v98, 0, v98
	v_mul_f32_e32 v99, 0x3f317217, v96
	v_fma_f32 v99, v96, s79, -v99
	v_fmac_f32_e32 v99, 0x3377d1cf, v96
	v_fmac_f32_e32 v99, 0x3f317217, v96
	v_mov_b32_e32 v96, v99
	v_add_f32_e32 v96, v98, v96
	v_xor_b32_e32 v99, 0x80000000, v96
.LBB0_751:
	s_or_b64 exec, exec, s[16:17]
	v_or_b32_e32 v96, 2, v101
	v_cmp_lt_i32_e64 s[14:15], v96, v82
	s_and_saveexec_b64 s[18:19], s[14:15]
	s_cbranch_execz .LBB0_753
	v_mul_f32_e64 v96, |v78|, s76
	v_exp_f32_e32 v96, v96
	s_nop 0
	v_add_f32_e32 v96, 1.0, v96
	v_log_f32_e32 v96, v96
	v_max_f32_e32 v97, v78, v78
	v_max_f32_e32 v97, 0, v97
	v_mul_f32_e32 v98, 0x3f317217, v96
	v_fma_f32 v98, v96, s79, -v98
	v_fmac_f32_e32 v98, 0x3377d1cf, v96
	v_fmac_f32_e32 v98, 0x3f317217, v96
	v_mov_b32_e32 v96, v98
	v_add_f32_e32 v96, v97, v96
	v_xor_b32_e32 v97, 0x80000000, v96
.LBB0_753:
	s_or_b64 exec, exec, s[18:19]
	v_or_b32_e32 v96, 3, v101
	v_cmp_lt_i32_e64 s[16:17], v96, v82
	v_mov_b32_e32 v103, 0
	v_mov_b32_e32 v96, 0
	s_and_saveexec_b64 s[20:21], s[16:17]
	s_cbranch_execz .LBB0_755
	v_mul_f32_e64 v96, |v79|, s76
	v_exp_f32_e32 v96, v96
	s_nop 0
	v_add_f32_e32 v96, 1.0, v96
	v_log_f32_e32 v96, v96
	v_max_f32_e32 v98, v79, v79
	v_max_f32_e32 v98, 0, v98
	v_mul_f32_e32 v100, 0x3f317217, v96
	v_fma_f32 v100, v96, s79, -v100
	v_fmac_f32_e32 v100, 0x3377d1cf, v96
	v_fmac_f32_e32 v100, 0x3f317217, v96
	v_mov_b32_e32 v96, v100
	v_add_f32_e32 v96, v98, v96
	v_xor_b32_e32 v96, 0x80000000, v96
.LBB0_755:
	s_or_b64 exec, exec, s[20:21]
	v_or_b32_e32 v98, 16, v101
	v_cmp_lt_i32_e64 s[18:19], v98, v82
	s_and_saveexec_b64 s[22:23], s[18:19]
	s_cbranch_execz .LBB0_757
	v_mul_f32_e64 v98, |v72|, s76
	v_exp_f32_e32 v98, v98
	s_nop 0
	v_add_f32_e32 v98, 1.0, v98
	v_log_f32_e32 v98, v98
	v_max_f32_e32 v100, v72, v72
	v_max_f32_e32 v100, 0, v100
	v_mul_f32_e32 v102, 0x3f317217, v98
	v_fma_f32 v102, v98, s79, -v102
	v_fmac_f32_e32 v102, 0x3377d1cf, v98
	v_fmac_f32_e32 v102, 0x3f317217, v98
	v_mov_b32_e32 v98, v102
	v_add_f32_e32 v98, v100, v98
	v_xor_b32_e32 v103, 0x80000000, v98
.LBB0_757:
	s_or_b64 exec, exec, s[22:23]
	v_or_b32_e32 v98, 17, v101
	v_cmp_lt_i32_e64 s[20:21], v98, v82
	v_mov_b32_e32 v121, 0
	v_mov_b32_e32 v120, 0
	s_and_saveexec_b64 s[24:25], s[20:21]
	s_cbranch_execz .LBB0_759
	v_mul_f32_e64 v98, |v73|, s76
	v_exp_f32_e32 v98, v98
	s_nop 0
	v_add_f32_e32 v98, 1.0, v98
	v_log_f32_e32 v98, v98
	v_max_f32_e32 v100, v73, v73
	v_max_f32_e32 v100, 0, v100
	v_mul_f32_e32 v102, 0x3f317217, v98
	v_fma_f32 v102, v98, s79, -v102
	v_fmac_f32_e32 v102, 0x3377d1cf, v98
	v_fmac_f32_e32 v102, 0x3f317217, v98
	v_mov_b32_e32 v98, v102
	v_add_f32_e32 v98, v100, v98
	v_xor_b32_e32 v120, 0x80000000, v98
; __device__ __forceinline__ float softplusf_(float v) { return fmaxf(v, 0.f) + __logf(1.f + __expf(-fabsf(v))); }
; __device__ void attn_item(const Params& p, int item, u16* O) {
;     ...
;       for (int mf = 0; mf < 4; ++mf) {
; #pragma unroll
;         for (int r = 0; r < 4; ++r) {
;           int kk = kt * 64 + mf * 16 + g4 * 4 + r;
;           valid[mf][r] = kk < qrow;
;           c[mf][r] = valid[mf][r] ? -softplusf_(s[mf][r]) : 0.f;
;         }
.LBB0_759:
	s_or_b64 exec, exec, s[24:25]
	v_or_b32_e32 v98, 18, v101
	v_cmp_lt_i32_e64 s[22:23], v98, v82
	s_and_saveexec_b64 s[26:27], s[22:23]
	s_cbranch_execz .LBB0_761
	v_mul_f32_e64 v98, |v74|, s76
	v_exp_f32_e32 v98, v98
	s_nop 0
	v_add_f32_e32 v98, 1.0, v98
	v_log_f32_e32 v98, v98
	v_max_f32_e32 v100, v74, v74
	v_max_f32_e32 v100, 0, v100
	v_mul_f32_e32 v102, 0x3f317217, v98
	v_fma_f32 v102, v98, s79, -v102
	v_fmac_f32_e32 v102, 0x3377d1cf, v98
	v_fmac_f32_e32 v102, 0x3f317217, v98
	v_mov_b32_e32 v98, v102
	v_add_f32_e32 v98, v100, v98
	v_xor_b32_e32 v121, 0x80000000, v98
.LBB0_761:
	s_or_b64 exec, exec, s[26:27]
	v_or_b32_e32 v98, 19, v101
	v_cmp_lt_i32_e64 s[24:25], v98, v82
	v_mov_b32_e32 v122, 0
	v_mov_b32_e32 v98, 0
	s_and_saveexec_b64 s[28:29], s[24:25]
	s_cbranch_execz .LBB0_763
	v_mul_f32_e64 v98, |v75|, s76
	v_exp_f32_e32 v98, v98
	s_nop 0
	v_add_f32_e32 v98, 1.0, v98
	v_log_f32_e32 v98, v98
	v_max_f32_e32 v100, v75, v75
	v_max_f32_e32 v100, 0, v100
	v_mul_f32_e32 v102, 0x3f317217, v98
	v_fma_f32 v102, v98, s79, -v102
	v_fmac_f32_e32 v102, 0x3377d1cf, v98
	v_fmac_f32_e32 v102, 0x3f317217, v98
	v_mov_b32_e32 v98, v102
	v_add_f32_e32 v98, v100, v98
	v_xor_b32_e32 v98, 0x80000000, v98
.LBB0_763:
	s_or_b64 exec, exec, s[28:29]
	v_or_b32_e32 v100, 32, v101
	v_cmp_lt_i32_e64 s[26:27], v100, v82
	s_and_saveexec_b64 s[30:31], s[26:27]
	s_cbranch_execz .LBB0_765
	v_mul_f32_e64 v100, |v68|, s76
	v_exp_f32_e32 v100, v100
	s_nop 0
	v_add_f32_e32 v100, 1.0, v100
	v_log_f32_e32 v100, v100
	v_max_f32_e32 v102, v68, v68
	v_max_f32_e32 v102, 0, v102
	v_mul_f32_e32 v122, 0x3f317217, v100
	v_fma_f32 v122, v100, s79, -v122
	v_fmac_f32_e32 v122, 0x3377d1cf, v100
	v_fmac_f32_e32 v122, 0x3f317217, v100
	v_mov_b32_e32 v100, v122
	v_add_f32_e32 v100, v102, v100
	v_xor_b32_e32 v122, 0x80000000, v100
.LBB0_765:
	s_or_b64 exec, exec, s[30:31]
	v_or_b32_e32 v100, 33, v101
	v_cmp_lt_i32_e64 s[28:29], v100, v82
	v_mov_b32_e32 v124, 0
	v_mov_b32_e32 v123, 0
	s_and_saveexec_b64 s[34:35], s[28:29]
	s_cbranch_execz .LBB0_767
	v_mul_f32_e64 v100, |v69|, s76
	v_exp_f32_e32 v100, v100
	s_nop 0
	v_add_f32_e32 v100, 1.0, v100
	v_log_f32_e32 v100, v100
	v_max_f32_e32 v102, v69, v69
	v_max_f32_e32 v102, 0, v102
	v_mul_f32_e32 v123, 0x3f317217, v100
	v_fma_f32 v123, v100, s79, -v123
	v_fmac_f32_e32 v123, 0x3377d1cf, v100
	v_fmac_f32_e32 v123, 0x3f317217, v100
	v_mov_b32_e32 v100, v123
	v_add_f32_e32 v100, v102, v100
	v_xor_b32_e32 v123, 0x80000000, v100
.LBB0_767:
	s_or_b64 exec, exec, s[34:35]
	v_or_b32_e32 v100, 34, v101
	v_cmp_lt_i32_e64 s[30:31], v100, v82
	s_and_saveexec_b64 s[36:37], s[30:31]
	s_cbranch_execz .LBB0_769
	v_mul_f32_e64 v100, |v70|, s76
	v_exp_f32_e32 v100, v100
	s_nop 0
	v_add_f32_e32 v100, 1.0, v100
	v_log_f32_e32 v100, v100
	v_max_f32_e32 v102, v70, v70
	v_max_f32_e32 v102, 0, v102
	v_mul_f32_e32 v124, 0x3f317217, v100
	v_fma_f32 v124, v100, s79, -v124
	v_fmac_f32_e32 v124, 0x3377d1cf, v100
	v_fmac_f32_e32 v124, 0x3f317217, v100
	v_mov_b32_e32 v100, v124
	v_add_f32_e32 v100, v102, v100
	v_xor_b32_e32 v124, 0x80000000, v100
.LBB0_769:
	s_or_b64 exec, exec, s[36:37]
	v_or_b32_e32 v100, 35, v101
	v_cmp_lt_i32_e64 s[34:35], v100, v82
	v_mov_b32_e32 v125, 0
	v_mov_b32_e32 v100, 0
	s_and_saveexec_b64 s[38:39], s[34:35]
	s_cbranch_execz .LBB0_771
	v_mul_f32_e64 v100, |v71|, s76
	v_exp_f32_e32 v100, v100
	s_nop 0
	v_add_f32_e32 v100, 1.0, v100
	v_log_f32_e32 v100, v100
	v_max_f32_e32 v102, v71, v71
	v_max_f32_e32 v102, 0, v102
	v_mul_f32_e32 v126, 0x3f317217, v100
	v_fma_f32 v126, v100, s79, -v126
	v_fmac_f32_e32 v126, 0x3377d1cf, v100
	v_fmac_f32_e32 v126, 0x3f317217, v100
	v_mov_b32_e32 v100, v126
	v_add_f32_e32 v100, v102, v100
	v_xor_b32_e32 v100, 0x80000000, v100
.LBB0_771:
	s_or_b64 exec, exec, s[38:39]
	v_or_b32_e32 v102, 48, v101
	v_cmp_lt_i32_e64 s[36:37], v102, v82
	s_and_saveexec_b64 s[40:41], s[36:37]
	s_cbranch_execz .LBB0_773
	v_mul_f32_e64 v102, |v64|, s76
	v_exp_f32_e32 v102, v102
	s_nop 0
	v_add_f32_e32 v102, 1.0, v102
	v_log_f32_e32 v102, v102
	v_max_f32_e32 v125, v64, v64
	v_max_f32_e32 v125, 0, v125
	v_mul_f32_e32 v126, 0x3f317217, v102
	v_fma_f32 v126, v102, s79, -v126
	v_fmac_f32_e32 v126, 0x3377d1cf, v102
	v_fmac_f32_e32 v126, 0x3f317217, v102
	v_mov_b32_e32 v102, v126
	v_add_f32_e32 v102, v125, v102
	v_xor_b32_e32 v125, 0x80000000, v102
.LBB0_773:
	s_or_b64 exec, exec, s[40:41]
	v_or_b32_e32 v102, 49, v101
	v_cmp_lt_i32_e64 s[38:39], v102, v82
	v_mov_b32_e32 v127, 0
	v_mov_b32_e32 v126, 0
	s_and_saveexec_b64 s[42:43], s[38:39]
	s_cbranch_execz .LBB0_775
	v_mul_f32_e64 v102, |v65|, s76
	v_exp_f32_e32 v102, v102
	s_nop 0
	v_add_f32_e32 v102, 1.0, v102
	v_log_f32_e32 v102, v102
	v_max_f32_e32 v126, v65, v65
	v_max_f32_e32 v126, 0, v126
	v_mul_f32_e32 v128, 0x3f317217, v102
	v_fma_f32 v128, v102, s79, -v128
	v_fmac_f32_e32 v128, 0x3377d1cf, v102
	v_fmac_f32_e32 v128, 0x3f317217, v102
	v_mov_b32_e32 v102, v128
	v_add_f32_e32 v102, v126, v102
	v_xor_b32_e32 v126, 0x80000000, v102
.LBB0_775:
	s_or_b64 exec, exec, s[42:43]
	v_or_b32_e32 v102, 50, v101
	v_cmp_lt_i32_e64 s[40:41], v102, v82
	s_and_saveexec_b64 s[48:49], s[40:41]
	s_cbranch_execz .LBB0_777
	v_mul_f32_e64 v102, |v66|, s76
	v_exp_f32_e32 v102, v102
	s_nop 0
	v_add_f32_e32 v102, 1.0, v102
	v_log_f32_e32 v102, v102
	v_max_f32_e32 v127, v66, v66
	v_max_f32_e32 v127, 0, v127
	v_mul_f32_e32 v128, 0x3f317217, v102
	v_fma_f32 v128, v102, s79, -v128
	v_fmac_f32_e32 v128, 0x3377d1cf, v102
	v_fmac_f32_e32 v128, 0x3f317217, v102
	v_mov_b32_e32 v102, v128
	v_add_f32_e32 v102, v127, v102
	v_xor_b32_e32 v127, 0x80000000, v102
.LBB0_777:
	s_or_b64 exec, exec, s[48:49]
	v_or_b32_e32 v101, 51, v101
	v_cmp_lt_i32_e64 s[42:43], v101, v82
	v_mov_b32_e32 v102, 0
	s_and_saveexec_b64 s[72:73], s[42:43]
	s_cbranch_execz .LBB0_779
	v_mul_f32_e64 v101, |v67|, s76
	v_exp_f32_e32 v101, v101
	s_nop 0
	v_add_f32_e32 v101, 1.0, v101
	v_log_f32_e32 v101, v101
	v_max_f32_e32 v102, v67, v67
	v_max_f32_e32 v102, 0, v102
	v_mul_f32_e32 v128, 0x3f317217, v101
	v_fma_f32 v128, v101, s79, -v128
	v_fmac_f32_e32 v128, 0x3377d1cf, v101
	v_fmac_f32_e32 v128, 0x3f317217, v101
	v_mov_b32_e32 v101, v128
	v_add_f32_e32 v101, v102, v101
	v_xor_b32_e32 v102, 0x80000000, v101
